# P4 scan: one static s_setprio 2 for the two compute waves (waves 0-1) of the scan workgroups, reset at scan exit
# baseline (speedup 1.0000x reference)
.Lp4_after_swa:
	s_cmpk_lg_i32 s33, 0x100
	s_load_dwordx2 s[26:27], s[0:1], 0xd8
	s_cselect_b64 s[4:5], -1, 0
	s_cmpk_lt_u32 s2, 0x80
	s_cselect_b64 s[6:7], -1, 0
	s_or_b64 s[8:9], s[6:7], s[4:5]
	v_bfe_u32 v2, v0, 6, 4
	v_and_b32_e32 v159, 0x3ff, v0
	s_movk_i32 s3, 0x80
	v_lshlrev_b32_e32 v152, 4, v2
	v_bfe_u32 v2, v0, 4, 2
	s_cmpk_lt_i32 s2, 0x80
	v_cmp_gt_u32_e64 s[4:5], s3, v159
	v_lshlrev_b32_e32 v126, 4, v159
	v_lshlrev_b32_e32 v161, 3, v2
	s_cselect_b64 s[30:31], -1, 0
	s_mov_b64 s[6:7], -1
	s_and_b64 vcc, exec, s[8:9]
	s_cbranch_vccz .LBB0_691
	s_andn2_b64 vcc, exec, s[30:31]
	s_cbranch_vccnz .LBB0_690
	v_lshlrev_b32_e32 v2, 4, v1
	s_waitcnt lgkmcnt(0)
	s_add_u32 s3, s26, 0x15b38000
	v_add_u32_e32 v155, 0, v2
	v_bfe_u32 v2, v0, 6, 4
	v_and_b32_e32 v6, 15, v0
	s_addc_u32 s23, s27, 0
	v_lshlrev_b32_e32 v2, 11, v2
	v_lshlrev_b32_e32 v3, 7, v6
	s_add_i32 s8, 0, 0x1d000
	v_add3_u32 v4, 0, v2, v3
	v_add3_u32 v3, s8, v2, v3
	v_bfe_u32 v2, v0, 4, 2
	v_mov_b32_e32 v131, 0
	s_movk_i32 s6, 0x100
	v_add_u32_e32 v153, 0, v126
	v_lshlrev_b32_e32 v2, 9, v2
	v_mul_u32_u24_e32 v128, 0x12100, v1
	v_mov_b32_e32 v129, v131
	v_cmp_gt_u32_e64 s[6:7], s6, v159
	v_mov_b32_e32 v127, v131
	v_add_u32_e32 v154, 0xf000, v153
	v_add_u32_e32 v156, 0xf000, v155
	v_or_b32_e32 v132, 0x4000, v126
	v_mov_b32_e32 v133, v131
	v_or_b32_e32 v134, 0x8000, v126
	v_mov_b32_e32 v135, v131
	v_or_b32_e32 v136, 0xc000, v126
	v_mov_b32_e32 v137, v131
	s_lshl_b32 s28, s2, 2
	s_lshl_b32 s29, s33, 2
	s_mov_b32 s34, 0x12000
	s_movk_i32 s35, 0x2000
	s_mov_b32 s36, 0x63b9000
	s_mov_b32 s37, 0x63bb000
	s_mov_b32 s38, 0x63c9000
	s_mov_b32 s39, 0x63cb000
	s_mov_b32 s40, 0x63d9000
	s_mov_b32 s41, 0x63db000
	s_mov_b32 s42, 0x63e8000
	s_mov_b32 s43, 0x63f9000
	s_mov_b32 s44, 0x63fb000
	s_mov_b32 s45, 0x6409000
	s_mov_b32 s46, 0x640b000
	s_mov_b32 s47, 0x6419000
	s_mov_b32 s48, 0x641b000
	s_mov_b32 s49, 0x6429000
	s_mov_b32 s50, 0x642b000
	s_mov_b64 s[8:9], 0x24200
	s_mov_b64 s[10:11], 0x80000
	v_lshlrev_b32_e32 v130, 2, v6
	v_lshlrev_b32_e32 v138, 2, v2
	s_mov_b64 s[12:13], 0x8424000
	s_mov_b32 s51, 0x8424000
	s_mov_b32 s52, 0x8426000
	s_mov_b32 s53, 0x8428000
	s_mov_b32 s54, 0x842a000
	s_mov_b32 s55, 0x842c000
	s_mov_b32 s56, 0x842e000
	v_add_u32_e32 v157, v4, v161
	v_add_u32_e32 v158, v3, v161
	s_mov_b32 s57, s2
	v_mov_b32_e32 v160, v252
	s_and_b64 vcc, exec, s[4:5]
	s_cbranch_vccz .Lp4_prio_done
	s_setprio 2
.Lp4_prio_done:
	s_branch .LBB0_662
.LBB0_661:
	s_or_b64 exec, exec, s[16:17]
	s_add_i32 s57, s57, s33
	s_add_i32 s28, s28, s29
	s_cmpk_lt_i32 s57, 0x80
	s_cbranch_scc0 .LBB0_690

.LBB0_690:
	s_setprio 0
	s_mov_b64 s[6:7], 0
